# speedup vs baseline: 1.0399x; 1.0009x over previous
; __device__ __forceinline__ uint4 epi_read(int row, int c16) {
;     const int k = row & 15;
;     uint4 v = *reinterpret_cast<const uint4*>((const char*)shm + row * 512 + ((c16 ^ (k >> 1)) << 4));
;     if (k & 1) v = make_uint4(v.z, v.w, v.x, v.y);
;     return v;
; }
.LBB0_398:
	v_lshrrev_b32_e32 v33, 1, v63
	v_bitop3_b32 v33, v33, v62, 7 bitop3:0x6c
	v_lshlrev_b32_e32 v33, 4, v33
	v_add_u32_e32 v33, v65, v33
	ds_read_b128 v[66:69], v33
	s_add_i32 s6, 0, 0x20000
	s_waitcnt vmcnt(7)
	v_bfe_u32 v70, v60, 16, 8
	v_bfe_u32 v53, v60, 8, 8
	v_lshl_add_u32 v72, v70, 2, s6
	s_waitcnt lgkmcnt(0)
	v_cndmask_b32_e64 v37, v66, v68, s[4:5]
	v_cndmask_b32_e64 v41, v67, v69, s[4:5]
	v_cndmask_b32_e64 v45, v69, v67, s[4:5]
	v_cndmask_b32_e64 v49, v68, v66, s[4:5]
	ds_read_b128 v[80:83], v33 offset:8192
	v_lshlrev_b32_e32 v66, 16, v37
	v_and_b32_e32 v67, 0xffff0000, v37
	v_and_b32_e32 v37, 0xff, v60
	v_bfe_u32 v70, v61, 16, 8
	v_lshrrev_b32_e32 v60, 24, v60
	v_lshlrev_b32_e32 v68, 16, v41
	v_and_b32_e32 v69, 0xffff0000, v41
	v_lshl_add_u32 v37, v37, 2, s6
	v_and_b32_e32 v41, 0xff, v61
	v_bfe_u32 v57, v61, 8, 8
	v_lshl_add_u32 v73, v70, 2, s6
	v_lshl_add_u32 v75, v60, 2, s6
	v_lshrrev_b32_e32 v60, 24, v61
	v_lshl_add_u32 v41, v41, 2, s6
	v_lshl_add_u32 v53, v53, 2, s6
	v_lshl_add_u32 v57, v57, 2, s6
	v_lshl_add_u32 v76, v60, 2, s6
	ds_read_b32 v60, v37
	ds_read_b32 v70, v41
	ds_read_b32 v61, v53
	ds_read_b32 v71, v57
	ds_read_b32 v72, v72
	ds_read_b32 v74, v73
	ds_read_b32 v73, v75
	ds_read_b32 v75, v76
	v_lshlrev_b32_e32 v76, 16, v28
	v_and_b32_e32 v77, 0xffff0000, v28
	v_lshlrev_b32_e32 v78, 16, v49
	v_and_b32_e32 v79, 0xffff0000, v49
	s_waitcnt lgkmcnt(5)
	v_pk_fma_f32 v[60:61], v[60:61], v[78:79], v[76:77]
	v_lshlrev_b32_e32 v28, 16, v29
	v_and_b32_e32 v29, 0xffff0000, v29
	v_lshlrev_b32_e32 v76, 16, v45
	v_and_b32_e32 v77, 0xffff0000, v45
	s_waitcnt lgkmcnt(1)
	v_pk_fma_f32 v[72:73], v[72:73], v[76:77], v[28:29]
	v_lshlrev_b32_e32 v28, 16, v30
	v_and_b32_e32 v29, 0xffff0000, v30
	v_pk_fma_f32 v[66:67], v[70:71], v[66:67], v[28:29]
	v_lshlrev_b32_e32 v28, 16, v31
	v_and_b32_e32 v29, 0xffff0000, v31
	s_waitcnt lgkmcnt(0)
	v_pk_fma_f32 v[68:69], v[74:75], v[68:69], v[28:29]
	v_cvt_pk_bf16_f32 v28, v60, v61
	v_cvt_pk_bf16_f32 v29, v72, v73
	v_cvt_pk_bf16_f32 v30, v66, v67
	v_cvt_pk_bf16_f32 v31, v68, v69
	s_mov_b64 s[0:1], -1
	s_and_b64 vcc, exec, s[16:17]
	s_cbranch_vccz .LBB0_400
	global_store_dwordx4 v128, v[28:31], s[12:13]
	s_mov_b64 s[0:1], 0

; __device__ __forceinline__ uint4 epi_read(int row, int c16) {
;     const int k = row & 15;
;     uint4 v = *reinterpret_cast<const uint4*>((const char*)shm + row * 512 + ((c16 ^ (k >> 1)) << 4));
;     if (k & 1) v = make_uint4(v.z, v.w, v.x, v.y);
;     return v;
; }
.LBB0_402:
	s_waitcnt vmcnt(7)
	v_bfe_u32 v60, v58, 16, 8
	v_bfe_u32 v53, v58, 8, 8
	v_lshl_add_u32 v66, v60, 2, s6
	v_bfe_u32 v60, v59, 16, 8
	s_waitcnt lgkmcnt(0)
	v_cndmask_b32_e64 v37, v80, v82, s[4:5]
	v_cndmask_b32_e64 v41, v81, v83, s[4:5]
	v_cndmask_b32_e64 v45, v83, v81, s[4:5]
	v_cndmask_b32_e64 v49, v82, v80, s[4:5]
	ds_read_b128 v[84:87], v33 offset:16384
	v_lshlrev_b32_e32 v28, 16, v37
	v_and_b32_e32 v29, 0xffff0000, v37
	v_and_b32_e32 v37, 0xff, v58
	v_lshrrev_b32_e32 v58, 24, v58
	v_lshlrev_b32_e32 v30, 16, v41
	v_and_b32_e32 v31, 0xffff0000, v41
	v_lshl_add_u32 v37, v37, 2, s6
	v_and_b32_e32 v41, 0xff, v59
	v_bfe_u32 v57, v59, 8, 8
	v_lshl_add_u32 v67, v60, 2, s6
	v_lshl_add_u32 v69, v58, 2, s6
	v_lshrrev_b32_e32 v58, 24, v59
	v_lshl_add_u32 v41, v41, 2, s6
	v_lshl_add_u32 v53, v53, 2, s6
	v_lshl_add_u32 v57, v57, 2, s6
	v_lshl_add_u32 v70, v58, 2, s6
	ds_read_b32 v58, v37
	ds_read_b32 v60, v41
	ds_read_b32 v59, v53
	ds_read_b32 v61, v57
	ds_read_b32 v66, v66
	ds_read_b32 v68, v67
	ds_read_b32 v67, v69
	ds_read_b32 v69, v70
	v_lshlrev_b32_e32 v70, 16, v24
	v_and_b32_e32 v71, 0xffff0000, v24
	v_lshlrev_b32_e32 v72, 16, v49
	v_and_b32_e32 v73, 0xffff0000, v49
	s_waitcnt lgkmcnt(5)
	v_pk_fma_f32 v[58:59], v[58:59], v[72:73], v[70:71]
	v_lshlrev_b32_e32 v24, 16, v25
	v_and_b32_e32 v25, 0xffff0000, v25
	v_lshlrev_b32_e32 v70, 16, v45
	v_and_b32_e32 v71, 0xffff0000, v45
	s_waitcnt lgkmcnt(1)
	v_pk_fma_f32 v[66:67], v[66:67], v[70:71], v[24:25]
	v_lshlrev_b32_e32 v24, 16, v26
	v_and_b32_e32 v25, 0xffff0000, v26
	v_pk_fma_f32 v[28:29], v[60:61], v[28:29], v[24:25]
	v_lshlrev_b32_e32 v24, 16, v27
	v_and_b32_e32 v25, 0xffff0000, v27
	s_waitcnt lgkmcnt(0)
	v_pk_fma_f32 v[30:31], v[68:69], v[30:31], v[24:25]
	v_cvt_pk_bf16_f32 v24, v58, v59
	v_cvt_pk_bf16_f32 v25, v66, v67
	v_cvt_pk_bf16_f32 v26, v28, v29
	v_cvt_pk_bf16_f32 v27, v30, v31
	s_mov_b64 s[0:1], -1
	s_and_b64 vcc, exec, s[16:17]
	s_cbranch_vccz .LBB0_404
	global_store_dwordx4 v56, v[24:27], s[12:13]
	s_mov_b64 s[0:1], 0

; __device__ __forceinline__ uint4 epi_read(int row, int c16) {
;     const int k = row & 15;
;     uint4 v = *reinterpret_cast<const uint4*>((const char*)shm + row * 512 + ((c16 ^ (k >> 1)) << 4));
;     if (k & 1) v = make_uint4(v.z, v.w, v.x, v.y);
;     return v;
; }
.LBB0_406:
	s_waitcnt vmcnt(7)
	v_bfe_u32 v30, v54, 8, 8
	v_lshl_add_u32 v31, v30, 2, s6
	v_bfe_u32 v30, v55, 8, 8
	v_lshl_add_u32 v45, v30, 2, s6
	v_bfe_u32 v30, v54, 16, 8
	s_waitcnt lgkmcnt(0)
	v_cndmask_b32_e64 v28, v84, v86, s[4:5]
	v_cndmask_b32_e64 v29, v85, v87, s[4:5]
	v_lshl_add_u32 v49, v30, 2, s6
	v_bfe_u32 v30, v55, 16, 8
	v_cndmask_b32_e64 v37, v87, v85, s[4:5]
	v_cndmask_b32_e64 v41, v86, v84, s[4:5]
	ds_read_b128 v[88:91], v33 offset:24576
	v_lshlrev_b32_e32 v24, 16, v28
	v_and_b32_e32 v25, 0xffff0000, v28
	v_lshlrev_b32_e32 v26, 16, v29
	v_and_b32_e32 v27, 0xffff0000, v29
	v_and_b32_e32 v28, 0xff, v54
	v_and_b32_e32 v29, 0xff, v55
	v_lshl_add_u32 v53, v30, 2, s6
	v_lshrrev_b32_e32 v30, 24, v54
	v_lshl_add_u32 v28, v28, 2, s6
	v_lshl_add_u32 v29, v29, 2, s6
	v_lshl_add_u32 v57, v30, 2, s6
	v_lshrrev_b32_e32 v30, 24, v55
	v_lshl_add_u32 v58, v30, 2, s6
	ds_read_b32 v28, v28
	ds_read_b32 v30, v29
	ds_read_b32 v29, v31
	ds_read_b32 v31, v45
	ds_read_b32 v54, v49
	ds_read_b32 v56, v53
	ds_read_b32 v55, v57
	ds_read_b32 v57, v58
	v_lshlrev_b32_e32 v58, 16, v20
	v_and_b32_e32 v59, 0xffff0000, v20
	v_lshlrev_b32_e32 v60, 16, v41
	v_and_b32_e32 v61, 0xffff0000, v41
	s_waitcnt lgkmcnt(5)
	v_pk_fma_f32 v[28:29], v[28:29], v[60:61], v[58:59]
	v_lshlrev_b32_e32 v20, 16, v21
	v_and_b32_e32 v21, 0xffff0000, v21
	v_lshlrev_b32_e32 v58, 16, v37
	v_and_b32_e32 v59, 0xffff0000, v37
	s_waitcnt lgkmcnt(1)
	v_pk_fma_f32 v[54:55], v[54:55], v[58:59], v[20:21]
	v_lshlrev_b32_e32 v20, 16, v22
	v_and_b32_e32 v21, 0xffff0000, v22
	v_pk_fma_f32 v[24:25], v[30:31], v[24:25], v[20:21]
	v_lshlrev_b32_e32 v20, 16, v23
	v_and_b32_e32 v21, 0xffff0000, v23
	s_waitcnt lgkmcnt(0)
	v_pk_fma_f32 v[26:27], v[56:57], v[26:27], v[20:21]
	v_cvt_pk_bf16_f32 v20, v28, v29
	v_cvt_pk_bf16_f32 v21, v54, v55
	v_cvt_pk_bf16_f32 v22, v24, v25
	v_cvt_pk_bf16_f32 v23, v26, v27
	s_mov_b64 s[0:1], -1
	s_and_b64 vcc, exec, s[16:17]
	s_cbranch_vccz .LBB0_408
	global_store_dwordx4 v52, v[20:23], s[12:13]
	s_mov_b64 s[0:1], 0

; __device__ __forceinline__ uint4 epi_read(int row, int c16) {
;     const int k = row & 15;
;     uint4 v = *reinterpret_cast<const uint4*>((const char*)shm + row * 512 + ((c16 ^ (k >> 1)) << 4));
;     if (k & 1) v = make_uint4(v.z, v.w, v.x, v.y);
;     return v;
; }
.LBB0_410:
	s_waitcnt vmcnt(7)
	v_bfe_u32 v26, v50, 8, 8
	v_lshl_add_u32 v27, v26, 2, s6
	v_bfe_u32 v26, v51, 8, 8
	v_lshl_add_u32 v28, v26, 2, s6
	v_bfe_u32 v26, v50, 16, 8
	s_waitcnt lgkmcnt(0)
	v_cndmask_b32_e64 v24, v88, v90, s[4:5]
	v_cndmask_b32_e64 v25, v89, v91, s[4:5]
	v_lshl_add_u32 v29, v26, 2, s6
	v_bfe_u32 v26, v51, 16, 8
	v_cndmask_b32_e64 v37, v91, v89, s[4:5]
	v_cndmask_b32_e64 v41, v90, v88, s[4:5]
	ds_read_b128 v[92:95], v33 offset:32768
	v_lshlrev_b32_e32 v20, 16, v24
	v_and_b32_e32 v21, 0xffff0000, v24
	v_lshlrev_b32_e32 v22, 16, v25
	v_and_b32_e32 v23, 0xffff0000, v25
	v_and_b32_e32 v24, 0xff, v50
	v_and_b32_e32 v25, 0xff, v51
	v_lshl_add_u32 v30, v26, 2, s6
	v_lshrrev_b32_e32 v26, 24, v50
	v_lshl_add_u32 v24, v24, 2, s6
	v_lshl_add_u32 v25, v25, 2, s6
	v_lshl_add_u32 v31, v26, 2, s6
	v_lshrrev_b32_e32 v26, 24, v51
	v_lshl_add_u32 v45, v26, 2, s6
	ds_read_b32 v24, v24
	ds_read_b32 v26, v25
	ds_read_b32 v25, v27
	ds_read_b32 v27, v28
	ds_read_b32 v28, v29
	ds_read_b32 v30, v30
	ds_read_b32 v29, v31
	ds_read_b32 v31, v45
	v_lshlrev_b32_e32 v50, 16, v16
	v_and_b32_e32 v51, 0xffff0000, v16
	v_lshlrev_b32_e32 v52, 16, v41
	v_and_b32_e32 v53, 0xffff0000, v41
	s_waitcnt lgkmcnt(5)
	v_pk_fma_f32 v[24:25], v[24:25], v[52:53], v[50:51]
	v_lshlrev_b32_e32 v16, 16, v17
	v_and_b32_e32 v17, 0xffff0000, v17
	v_lshlrev_b32_e32 v50, 16, v37
	v_and_b32_e32 v51, 0xffff0000, v37
	s_waitcnt lgkmcnt(1)
	v_pk_fma_f32 v[28:29], v[28:29], v[50:51], v[16:17]
	v_lshlrev_b32_e32 v16, 16, v18
	v_and_b32_e32 v17, 0xffff0000, v18
	v_pk_fma_f32 v[20:21], v[26:27], v[20:21], v[16:17]
	v_lshlrev_b32_e32 v16, 16, v19
	v_and_b32_e32 v17, 0xffff0000, v19
	s_waitcnt lgkmcnt(0)
	v_pk_fma_f32 v[22:23], v[30:31], v[22:23], v[16:17]
	v_cvt_pk_bf16_f32 v16, v24, v25
	v_cvt_pk_bf16_f32 v17, v28, v29
	v_cvt_pk_bf16_f32 v18, v20, v21
	v_cvt_pk_bf16_f32 v19, v22, v23
	s_mov_b64 s[0:1], -1
	s_and_b64 vcc, exec, s[16:17]
	s_cbranch_vccz .LBB0_412
	global_store_dwordx4 v48, v[16:19], s[12:13]
	s_mov_b64 s[0:1], 0

; __device__ __forceinline__ uint4 epi_read(int row, int c16) {
;     const int k = row & 15;
;     uint4 v = *reinterpret_cast<const uint4*>((const char*)shm + row * 512 + ((c16 ^ (k >> 1)) << 4));
;     if (k & 1) v = make_uint4(v.z, v.w, v.x, v.y);
;     return v;
; }
.LBB0_414:
	s_waitcnt vmcnt(7)
	v_bfe_u32 v22, v46, 8, 8
	v_lshl_add_u32 v23, v22, 2, s6
	v_bfe_u32 v22, v47, 8, 8
	v_lshl_add_u32 v24, v22, 2, s6
	v_bfe_u32 v22, v46, 16, 8
	s_waitcnt lgkmcnt(0)
	v_cndmask_b32_e64 v20, v92, v94, s[4:5]
	v_cndmask_b32_e64 v21, v93, v95, s[4:5]
	v_lshl_add_u32 v25, v22, 2, s6
	v_bfe_u32 v22, v47, 16, 8
	v_cndmask_b32_e64 v37, v95, v93, s[4:5]
	v_cndmask_b32_e64 v31, v94, v92, s[4:5]
	ds_read_b128 v[96:99], v33 offset:40960
	v_lshlrev_b32_e32 v16, 16, v20
	v_and_b32_e32 v17, 0xffff0000, v20
	v_lshlrev_b32_e32 v18, 16, v21
	v_and_b32_e32 v19, 0xffff0000, v21
	v_and_b32_e32 v20, 0xff, v46
	v_and_b32_e32 v21, 0xff, v47
	v_lshl_add_u32 v26, v22, 2, s6
	v_lshrrev_b32_e32 v22, 24, v46
	v_lshl_add_u32 v20, v20, 2, s6
	v_lshl_add_u32 v21, v21, 2, s6
	v_lshl_add_u32 v27, v22, 2, s6
	v_lshrrev_b32_e32 v22, 24, v47
	v_lshl_add_u32 v28, v22, 2, s6
	ds_read_b32 v20, v20
	ds_read_b32 v22, v21
	ds_read_b32 v21, v23
	ds_read_b32 v23, v24
	ds_read_b32 v24, v25
	ds_read_b32 v26, v26
	ds_read_b32 v25, v27
	ds_read_b32 v27, v28
	v_lshlrev_b32_e32 v28, 16, v12
	v_and_b32_e32 v29, 0xffff0000, v12
	v_lshlrev_b32_e32 v30, 16, v31
	v_and_b32_e32 v31, 0xffff0000, v31
	s_waitcnt lgkmcnt(5)
	v_pk_fma_f32 v[20:21], v[20:21], v[30:31], v[28:29]
	v_lshlrev_b32_e32 v12, 16, v13
	v_and_b32_e32 v13, 0xffff0000, v13
	v_lshlrev_b32_e32 v28, 16, v37
	v_and_b32_e32 v29, 0xffff0000, v37
	s_waitcnt lgkmcnt(1)
	v_pk_fma_f32 v[24:25], v[24:25], v[28:29], v[12:13]
	v_lshlrev_b32_e32 v12, 16, v14
	v_and_b32_e32 v13, 0xffff0000, v14
	v_pk_fma_f32 v[16:17], v[22:23], v[16:17], v[12:13]
	v_lshlrev_b32_e32 v12, 16, v15
	v_and_b32_e32 v13, 0xffff0000, v15
	s_waitcnt lgkmcnt(0)
	v_pk_fma_f32 v[18:19], v[26:27], v[18:19], v[12:13]
	v_cvt_pk_bf16_f32 v12, v20, v21
	v_cvt_pk_bf16_f32 v13, v24, v25
	v_cvt_pk_bf16_f32 v14, v16, v17
	v_cvt_pk_bf16_f32 v15, v18, v19
	s_mov_b64 s[0:1], -1
	s_and_b64 vcc, exec, s[16:17]
	s_cbranch_vccz .LBB0_416
	global_store_dwordx4 v44, v[12:15], s[12:13]
	s_mov_b64 s[0:1], 0

; __device__ __forceinline__ uint4 epi_read(int row, int c16) {
;     const int k = row & 15;
;     uint4 v = *reinterpret_cast<const uint4*>((const char*)shm + row * 512 + ((c16 ^ (k >> 1)) << 4));
;     if (k & 1) v = make_uint4(v.z, v.w, v.x, v.y);
;     return v;
; }
.LBB0_418:
	s_waitcnt vmcnt(7)
	v_bfe_u32 v18, v42, 8, 8
	v_lshl_add_u32 v19, v18, 2, s6
	v_bfe_u32 v18, v43, 8, 8
	v_lshl_add_u32 v20, v18, 2, s6
	v_bfe_u32 v18, v42, 16, 8
	s_waitcnt lgkmcnt(0)
	v_cndmask_b32_e64 v16, v96, v98, s[4:5]
	v_cndmask_b32_e64 v17, v97, v99, s[4:5]
	v_lshl_add_u32 v21, v18, 2, s6
	v_bfe_u32 v18, v43, 16, 8
	v_cndmask_b32_e64 v28, v99, v97, s[4:5]
	v_cndmask_b32_e64 v27, v98, v96, s[4:5]
	ds_read_b128 v[100:103], v33 offset:49152
	v_lshlrev_b32_e32 v12, 16, v16
	v_and_b32_e32 v13, 0xffff0000, v16
	v_lshlrev_b32_e32 v14, 16, v17
	v_and_b32_e32 v15, 0xffff0000, v17
	v_and_b32_e32 v16, 0xff, v42
	v_and_b32_e32 v17, 0xff, v43
	v_lshl_add_u32 v22, v18, 2, s6
	v_lshrrev_b32_e32 v18, 24, v42
	v_lshl_add_u32 v16, v16, 2, s6
	v_lshl_add_u32 v17, v17, 2, s6
	v_lshl_add_u32 v23, v18, 2, s6
	v_lshrrev_b32_e32 v18, 24, v43
	v_lshl_add_u32 v24, v18, 2, s6
	ds_read_b32 v16, v16
	ds_read_b32 v18, v17
	ds_read_b32 v17, v19
	ds_read_b32 v19, v20
	ds_read_b32 v20, v21
	ds_read_b32 v22, v22
	ds_read_b32 v21, v23
	ds_read_b32 v23, v24
	v_lshlrev_b32_e32 v24, 16, v8
	v_and_b32_e32 v25, 0xffff0000, v8
	v_lshlrev_b32_e32 v26, 16, v27
	v_and_b32_e32 v27, 0xffff0000, v27
	s_waitcnt lgkmcnt(5)
	v_pk_fma_f32 v[16:17], v[16:17], v[26:27], v[24:25]
	v_lshlrev_b32_e32 v8, 16, v9
	v_and_b32_e32 v9, 0xffff0000, v9
	v_lshlrev_b32_e32 v24, 16, v28
	v_and_b32_e32 v25, 0xffff0000, v28
	s_waitcnt lgkmcnt(1)
	v_pk_fma_f32 v[20:21], v[20:21], v[24:25], v[8:9]
	v_lshlrev_b32_e32 v8, 16, v10
	v_and_b32_e32 v9, 0xffff0000, v10
	v_pk_fma_f32 v[12:13], v[18:19], v[12:13], v[8:9]
	v_lshlrev_b32_e32 v8, 16, v11
	v_and_b32_e32 v9, 0xffff0000, v11
	s_waitcnt lgkmcnt(0)
	v_pk_fma_f32 v[14:15], v[22:23], v[14:15], v[8:9]
	v_cvt_pk_bf16_f32 v8, v16, v17
	v_cvt_pk_bf16_f32 v9, v20, v21
	v_cvt_pk_bf16_f32 v10, v12, v13
	v_cvt_pk_bf16_f32 v11, v14, v15
	s_mov_b64 s[0:1], -1
	s_and_b64 vcc, exec, s[16:17]
	s_cbranch_vccz .LBB0_420
	global_store_dwordx4 v40, v[8:11], s[12:13]
	s_mov_b64 s[0:1], 0

; __device__ __forceinline__ uint4 epi_read(int row, int c16) {
;     const int k = row & 15;
;     uint4 v = *reinterpret_cast<const uint4*>((const char*)shm + row * 512 + ((c16 ^ (k >> 1)) << 4));
;     if (k & 1) v = make_uint4(v.z, v.w, v.x, v.y);
;     return v;
; }
.LBB0_422:
	s_waitcnt vmcnt(7)
	v_bfe_u32 v14, v38, 8, 8
	v_lshl_add_u32 v15, v14, 2, s6
	v_bfe_u32 v14, v39, 8, 8
	v_lshl_add_u32 v16, v14, 2, s6
	v_bfe_u32 v14, v38, 16, 8
	s_waitcnt lgkmcnt(0)
	v_cndmask_b32_e64 v12, v100, v102, s[4:5]
	v_cndmask_b32_e64 v13, v101, v103, s[4:5]
	v_lshl_add_u32 v17, v14, 2, s6
	v_bfe_u32 v14, v39, 16, 8
	v_cndmask_b32_e64 v24, v103, v101, s[4:5]
	v_cndmask_b32_e64 v23, v102, v100, s[4:5]
	ds_read_b128 v[104:107], v33 offset:57344
	v_lshlrev_b32_e32 v8, 16, v12
	v_and_b32_e32 v9, 0xffff0000, v12
	v_lshlrev_b32_e32 v10, 16, v13
	v_and_b32_e32 v11, 0xffff0000, v13
	v_and_b32_e32 v12, 0xff, v38
	v_and_b32_e32 v13, 0xff, v39
	v_lshl_add_u32 v18, v14, 2, s6
	v_lshrrev_b32_e32 v14, 24, v38
	v_lshl_add_u32 v12, v12, 2, s6
	v_lshl_add_u32 v13, v13, 2, s6
	v_lshl_add_u32 v19, v14, 2, s6
	v_lshrrev_b32_e32 v14, 24, v39
	v_lshl_add_u32 v20, v14, 2, s6
	ds_read_b32 v12, v12
	ds_read_b32 v14, v13
	ds_read_b32 v13, v15
	ds_read_b32 v15, v16
	ds_read_b32 v16, v17
	ds_read_b32 v18, v18
	ds_read_b32 v17, v19
	ds_read_b32 v19, v20
	v_lshlrev_b32_e32 v20, 16, v4
	v_and_b32_e32 v21, 0xffff0000, v4
	v_lshlrev_b32_e32 v22, 16, v23
	v_and_b32_e32 v23, 0xffff0000, v23
	s_waitcnt lgkmcnt(5)
	v_pk_fma_f32 v[12:13], v[12:13], v[22:23], v[20:21]
	v_lshlrev_b32_e32 v4, 16, v5
	v_and_b32_e32 v5, 0xffff0000, v5
	v_lshlrev_b32_e32 v20, 16, v24
	v_and_b32_e32 v21, 0xffff0000, v24
	s_waitcnt lgkmcnt(1)
	v_pk_fma_f32 v[16:17], v[16:17], v[20:21], v[4:5]
	v_lshlrev_b32_e32 v4, 16, v6
	v_and_b32_e32 v5, 0xffff0000, v6
	v_pk_fma_f32 v[8:9], v[14:15], v[8:9], v[4:5]
	v_lshlrev_b32_e32 v4, 16, v7
	v_and_b32_e32 v5, 0xffff0000, v7
	s_waitcnt lgkmcnt(0)
	v_pk_fma_f32 v[10:11], v[18:19], v[10:11], v[4:5]
	v_cvt_pk_bf16_f32 v4, v12, v13
	v_cvt_pk_bf16_f32 v5, v16, v17
	v_cvt_pk_bf16_f32 v6, v8, v9
	v_cvt_pk_bf16_f32 v7, v10, v11
	s_mov_b64 s[0:1], -1
	s_and_b64 vcc, exec, s[16:17]
	s_cbranch_vccz .LBB0_424
	global_store_dwordx4 v36, v[4:7], s[12:13]
	s_mov_b64 s[0:1], 0

; __device__ __forceinline__ uint4 epi_read(int row, int c16) {
;     const int k = row & 15;
;     uint4 v = *reinterpret_cast<const uint4*>((const char*)shm + row * 512 + ((c16 ^ (k >> 1)) << 4));
;     if (k & 1) v = make_uint4(v.z, v.w, v.x, v.y);
;     return v;
; }
.LBB0_426:
	s_waitcnt vmcnt(7)
	v_bfe_u32 v10, v34, 8, 8
	v_lshl_add_u32 v11, v10, 2, s6
	v_bfe_u32 v10, v35, 8, 8
	v_lshl_add_u32 v12, v10, 2, s6
	v_bfe_u32 v10, v34, 16, 8
	s_waitcnt lgkmcnt(0)
	v_cndmask_b32_e64 v8, v104, v106, s[4:5]
	v_cndmask_b32_e64 v9, v105, v107, s[4:5]
	v_lshl_add_u32 v13, v10, 2, s6
	v_bfe_u32 v10, v35, 16, 8
	v_cndmask_b32_e64 v20, v107, v105, s[4:5]
	v_cndmask_b32_e64 v19, v106, v104, s[4:5]
	v_lshlrev_b32_e32 v4, 16, v8
	v_and_b32_e32 v5, 0xffff0000, v8
	v_lshlrev_b32_e32 v6, 16, v9
	v_and_b32_e32 v7, 0xffff0000, v9
	v_and_b32_e32 v8, 0xff, v34
	v_and_b32_e32 v9, 0xff, v35
	v_lshl_add_u32 v14, v10, 2, s6
	v_lshrrev_b32_e32 v10, 24, v34
	v_lshl_add_u32 v8, v8, 2, s6
	v_lshl_add_u32 v9, v9, 2, s6
	v_lshl_add_u32 v15, v10, 2, s6
	v_lshrrev_b32_e32 v10, 24, v35
	v_lshl_add_u32 v16, v10, 2, s6
	ds_read_b32 v8, v8
	ds_read_b32 v10, v9
	ds_read_b32 v9, v11
	ds_read_b32 v11, v12
	ds_read_b32 v12, v13
	ds_read_b32 v14, v14
	ds_read_b32 v13, v15
	ds_read_b32 v15, v16
	v_lshlrev_b32_e32 v16, 16, v0
	v_and_b32_e32 v17, 0xffff0000, v0
	v_lshlrev_b32_e32 v18, 16, v19
	v_and_b32_e32 v19, 0xffff0000, v19
	s_waitcnt lgkmcnt(5)
	v_pk_fma_f32 v[8:9], v[8:9], v[18:19], v[16:17]
	v_lshlrev_b32_e32 v0, 16, v1
	v_and_b32_e32 v1, 0xffff0000, v1
	v_lshlrev_b32_e32 v16, 16, v20
	v_and_b32_e32 v17, 0xffff0000, v20
	s_waitcnt lgkmcnt(1)
	v_pk_fma_f32 v[12:13], v[12:13], v[16:17], v[0:1]
	v_lshlrev_b32_e32 v0, 16, v2
	v_and_b32_e32 v1, 0xffff0000, v2
	v_pk_fma_f32 v[4:5], v[10:11], v[4:5], v[0:1]
	v_lshlrev_b32_e32 v0, 16, v3
	v_and_b32_e32 v1, 0xffff0000, v3
	s_waitcnt lgkmcnt(0)
	v_pk_fma_f32 v[6:7], v[14:15], v[6:7], v[0:1]
	v_cvt_pk_bf16_f32 v0, v8, v9
	v_cvt_pk_bf16_f32 v1, v12, v13
	v_cvt_pk_bf16_f32 v2, v4, v5
	v_cvt_pk_bf16_f32 v3, v6, v7
	s_mov_b64 s[0:1], -1
	s_and_b64 vcc, exec, s[16:17]
	s_cbranch_vccz .LBB0_428
	global_store_dwordx4 v32, v[0:3], s[12:13]
	s_mov_b64 s[0:1], 0
